# sweep loops: weights hoisted out of loop, first LDS fragments prefetched at end of previous iteration
# speedup vs baseline: 1.0049x; 1.0049x over previous
; #define LAS __attribute__((address_space(3)))
;     constexpr int SHIFT = 24 - 8 * (MODE & 3);
;     const int r32 = lane & 31, hi = lane >> 5, ql = 32 * (wid & 1) + r32;
;     LAS unsigned* hist = (LAS unsigned*)(lds + DS_HIST) + ql;   LAS unsigned short* sel = (LAS unsigned short*)(lds + DS_SEL) + ql * 256; LAS unsigned* cnt = (LAS unsigned*)(lds + DS_CNT) + ql;
;     LAS unsigned* cand = (LAS unsigned*)(lds + DS_CAND) + ql * DS_CAP; LAS unsigned* ccnt = (LAS unsigned*)(lds + DS_CCNT) + ql;
;     LAS const unsigned char* iqb = lds + DS_IQ + ql * 528 + hi * 16; LAS const float* wqb = (LAS const float*)(lds + DS_WQ) + ql;
;     const int kt0 = wid >> 1; const int nit = kt0 <= c ? 2 * ((c - kt0) / 4 + 1) : 0;
;     const float t_lo = bucket_lo((int)pref), t_hi = bucket_lo((int)pref + 1);
;     const bf16_t* ikp = Zb + (size_t)(64 * kt0 + r32) * NZ + ZIK + hi * 8;
;     bf16x8 a0, a1;
;     if (nit > 0) { a0 = *(const bf16x8*)ikp; a1 = *(const bf16x8*)(ikp + 16); }
; #pragma unroll 1
;     for (int it = 0; it < nit; ++it) {
;         const int kt = kt0 + 4 * (it >> 1), kb = it & 1;
;         const int itn = it + 1 < nit ? it + 1 : it;
;         const bf16_t* np = ikp + (size_t)(256 * (itn >> 1) + 32 * (itn & 1)) * NZ; const bf16x8 n0 = *(const bf16x8*)np, n1 = *(const bf16x8*)(np + 16);
;         f32x2v sc2[8];
; #pragma unroll
;         for (int r = 0; r < 8; ++r) sc2[r] = (f32x2v){0.f, 0.f};
;     ...
;         { f32x16 zero16;
; #pragma unroll
;           for (int r = 0; r < 16; ++r) zero16[r] = 0.f;
;           f32x16 dA0, dA1, dB0, dB1; float wA0, wA1, wB0, wB1;
;           SW_MF(0, dA0, dA1, wA0, wA1);
;           SW_MF(1, dB0, dB1, wB0, wB1); __builtin_amdgcn_sched_barrier(0);
;           SW_VA(dA0, dA1, wA0, wA1);    __builtin_amdgcn_sched_barrier(0);
;           SW_MF(2, dA0, dA1, wA0, wA1); __builtin_amdgcn_sched_barrier(0);
;           SW_VA(dB0, dB1, wB0, wB1);    __builtin_amdgcn_sched_barrier(0);
;           SW_MF(3, dB0, dB1, wB0, wB1); __builtin_amdgcn_sched_barrier(0);
;           SW_VA(dA0, dA1, wA0, wA1);    __builtin_amdgcn_sched_barrier(0);
;           SW_VA(dB0, dB1, wB0, wB1); }
.LBB0_979:
	v_add_u32_e32 v1, 0x200, v1
	v_cmp_lt_u32_e32 vcc, s62, v1
	ds_write_b32 v0, v155
	s_or_b64 s[0:1], vcc, s[0:1]
	v_add_u32_e32 v0, 0x800, v0
	s_andn2_b64 exec, exec, s[0:1]
	s_cbranch_execnz .LBB0_979
	s_or_b64 exec, exec, s[0:1]
	s_lshr_b32 s24, s3, 7
	v_mov_b32_e32 v0, s24
	v_sub_co_u32_e64 v0, s[18:19], s2, v0
	s_lshl_b32 s0, s69, 5
	v_readfirstlane_b32 s1, v0
	v_lshl_or_b32 v2, s24, 6, v151
	v_mov_b64_e32 v[0:1], s[36:37]
	v_and_or_b32 v169, s0, 32, v151
	s_lshr_b32 s1, s1, 1
	v_mad_u64_u32 v[0:1], s[2:3], v2, s61, v[0:1]
	v_lshlrev_b32_e32 v154, 1, v152
	v_lshlrev_b32_e32 v171, 2, v169
	s_and_b32 s25, s1, 0x7ffffffe
	v_lshl_add_u64 v[0:1], v[0:1], 0, v[154:155]
	s_mov_b64 s[2:3], 0x1300
	v_add_u32_e32 v230, 0x100, v171
	v_mad_u32_u24 v165, v169, s86, v199
	v_add_u32_e32 v167, s51, v171
	s_add_i32 s25, s25, 2
	v_lshl_add_u64 v[140:141], v[0:1], 0, s[2:3]
	s_and_b64 vcc, exec, s[18:19]
	s_waitcnt lgkmcnt(0)
	s_barrier
	s_cbranch_vccnz .LBB0_983
	global_load_dwordx4 v[76:79], v[140:141], off
	global_load_dwordx4 v[72:75], v[140:141], off offset:32
	s_mov_b32 s2, 0
	v_mov_b32_e32 v117, 0x280
	v_mov_b32_e32 v118, 0x2ff
	v_add_u32_e32 v116, 0xfffe0000, v230
	v_mov_b32_e32 v112, 0x2c800000
	v_mov_b32_e32 v113, 0x2c800000
	ds_read2st64_b32 v[80:81], v167 offset1:1
	ds_read2st64_b32 v[82:83], v167 offset0:2 offset1:3
	ds_read2st64_b32 v[84:85], v167 offset0:4 offset1:5
	ds_read2st64_b32 v[86:87], v167 offset0:6 offset1:7
	ds_read_b128 v[0:3], v165
	ds_read_b128 v[4:7], v165 offset:32
	ds_read_b128 v[8:11], v165 offset:64
	ds_read_b128 v[12:15], v165 offset:96
	s_waitcnt lgkmcnt(4)
	v_mov_b32_e32 v104, v81
	v_mov_b32_e32 v106, v83
	v_mov_b32_e32 v108, v85
	v_mov_b32_e32 v110, v87
	s_waitcnt vmcnt(0) lgkmcnt(0)
.Lm5_loop:
	v_mfma_f32_32x32x16_bf16 v[16:31], v[76:79], v[0:3], 0
	v_mfma_f32_32x32x16_bf16 v[16:31], v[72:75], v[4:7], v[16:31]
	ds_read_b128 v[0:3], v165 offset:128
	ds_read_b128 v[4:7], v165 offset:160
	v_mfma_f32_32x32x16_bf16 v[32:47], v[76:79], v[8:11], 0
	v_mfma_f32_32x32x16_bf16 v[32:47], v[72:75], v[12:15], v[32:47]
	ds_read_b128 v[8:11], v165 offset:192
	ds_read_b128 v[12:15], v165 offset:224
	s_add_i32 s1, s2, 1
	s_cmp_lt_u32 s1, s25
	s_cselect_b32 s3, s1, s2
	s_lshl_b32 vcc_lo, s3, 7
	s_and_b32 vcc_lo, vcc_lo, 0x7fffff00
	s_lshl_b32 s3, s3, 5
	s_and_b32 s3, s3, 32
	s_or_b32 s3, vcc_lo, s3
	v_mad_u64_u32 v[114:115], vcc, s3, v223, v[140:141]
	global_load_dwordx4 v[64:67], v[114:115], off
	global_load_dwordx4 v[68:71], v[114:115], off offset:32
	v_pk_mul_f32 v[16:17], v[16:17], v[112:113] clamp
	v_pk_mul_f32 v[18:19], v[18:19], v[112:113] clamp
	v_pk_mul_f32 v[20:21], v[20:21], v[112:113] clamp
	v_pk_mul_f32 v[22:23], v[22:23], v[112:113] clamp
	v_pk_mul_f32 v[24:25], v[24:25], v[112:113] clamp
	v_pk_mul_f32 v[26:27], v[26:27], v[112:113] clamp
	v_pk_mul_f32 v[28:29], v[28:29], v[112:113] clamp
	v_pk_mul_f32 v[30:31], v[30:31], v[112:113] clamp
	v_pk_fma_f32 v[88:89], v[16:17], v[80:81], 0 op_sel_hi:[1,0,0]
	v_pk_fma_f32 v[90:91], v[18:19], v[80:81], 0 op_sel_hi:[1,0,0]
	v_pk_fma_f32 v[92:93], v[20:21], v[80:81], 0 op_sel_hi:[1,0,0]
	v_pk_fma_f32 v[94:95], v[22:23], v[80:81], 0 op_sel_hi:[1,0,0]
	v_pk_fma_f32 v[96:97], v[24:25], v[80:81], 0 op_sel_hi:[1,0,0]
	v_pk_fma_f32 v[98:99], v[26:27], v[80:81], 0 op_sel_hi:[1,0,0]
	v_pk_fma_f32 v[100:101], v[28:29], v[80:81], 0 op_sel_hi:[1,0,0]
	v_pk_fma_f32 v[102:103], v[30:31], v[80:81], 0 op_sel_hi:[1,0,0]
	s_waitcnt lgkmcnt(2)
	v_mfma_f32_32x32x16_bf16 v[16:31], v[76:79], v[0:3], 0
	v_mfma_f32_32x32x16_bf16 v[16:31], v[72:75], v[4:7], v[16:31]
	ds_read_b128 v[0:3], v165 offset:256
	ds_read_b128 v[4:7], v165 offset:288
	v_pk_mul_f32 v[32:33], v[32:33], v[112:113] clamp
	v_pk_mul_f32 v[34:35], v[34:35], v[112:113] clamp
	v_pk_mul_f32 v[36:37], v[36:37], v[112:113] clamp
	v_pk_mul_f32 v[38:39], v[38:39], v[112:113] clamp
	v_pk_mul_f32 v[40:41], v[40:41], v[112:113] clamp
	v_pk_mul_f32 v[42:43], v[42:43], v[112:113] clamp
	v_pk_mul_f32 v[44:45], v[44:45], v[112:113] clamp
	v_pk_mul_f32 v[46:47], v[46:47], v[112:113] clamp
	v_pk_fma_f32 v[88:89], v[32:33], v[104:105], v[88:89] op_sel_hi:[1,0,1]
	v_pk_fma_f32 v[90:91], v[34:35], v[104:105], v[90:91] op_sel_hi:[1,0,1]
	v_pk_fma_f32 v[92:93], v[36:37], v[104:105], v[92:93] op_sel_hi:[1,0,1]
	v_pk_fma_f32 v[94:95], v[38:39], v[104:105], v[94:95] op_sel_hi:[1,0,1]
	v_pk_fma_f32 v[96:97], v[40:41], v[104:105], v[96:97] op_sel_hi:[1,0,1]
	v_pk_fma_f32 v[98:99], v[42:43], v[104:105], v[98:99] op_sel_hi:[1,0,1]
	v_pk_fma_f32 v[100:101], v[44:45], v[104:105], v[100:101] op_sel_hi:[1,0,1]
	v_pk_fma_f32 v[102:103], v[46:47], v[104:105], v[102:103] op_sel_hi:[1,0,1]
	s_waitcnt lgkmcnt(2)
	v_mfma_f32_32x32x16_bf16 v[32:47], v[76:79], v[8:11], 0
	v_mfma_f32_32x32x16_bf16 v[32:47], v[72:75], v[12:15], v[32:47]
	ds_read_b128 v[8:11], v165 offset:320
	ds_read_b128 v[12:15], v165 offset:352
	v_pk_mul_f32 v[16:17], v[16:17], v[112:113] clamp
	v_pk_mul_f32 v[18:19], v[18:19], v[112:113] clamp
	v_pk_mul_f32 v[20:21], v[20:21], v[112:113] clamp
	v_pk_mul_f32 v[22:23], v[22:23], v[112:113] clamp
	v_pk_mul_f32 v[24:25], v[24:25], v[112:113] clamp
	v_pk_mul_f32 v[26:27], v[26:27], v[112:113] clamp
	v_pk_mul_f32 v[28:29], v[28:29], v[112:113] clamp
	v_pk_mul_f32 v[30:31], v[30:31], v[112:113] clamp
	v_pk_fma_f32 v[88:89], v[16:17], v[82:83], v[88:89] op_sel_hi:[1,0,1]
	v_pk_fma_f32 v[90:91], v[18:19], v[82:83], v[90:91] op_sel_hi:[1,0,1]
	v_pk_fma_f32 v[92:93], v[20:21], v[82:83], v[92:93] op_sel_hi:[1,0,1]
	v_pk_fma_f32 v[94:95], v[22:23], v[82:83], v[94:95] op_sel_hi:[1,0,1]
	v_pk_fma_f32 v[96:97], v[24:25], v[82:83], v[96:97] op_sel_hi:[1,0,1]
	v_pk_fma_f32 v[98:99], v[26:27], v[82:83], v[98:99] op_sel_hi:[1,0,1]
	v_pk_fma_f32 v[100:101], v[28:29], v[82:83], v[100:101] op_sel_hi:[1,0,1]
	v_pk_fma_f32 v[102:103], v[30:31], v[82:83], v[102:103] op_sel_hi:[1,0,1]
	s_waitcnt lgkmcnt(2)
;     ...
;         { f32x16 zero16;
; #pragma unroll
;           for (int r = 0; r < 16; ++r) zero16[r] = 0.f;
;           f32x16 dA0, dA1, dB0, dB1; float wA0, wA1, wB0, wB1;
;           SW_MF(0, dA0, dA1, wA0, wA1);
;           SW_MF(1, dB0, dB1, wB0, wB1); __builtin_amdgcn_sched_barrier(0);
;           SW_VA(dA0, dA1, wA0, wA1);    __builtin_amdgcn_sched_barrier(0);
;           SW_MF(2, dA0, dA1, wA0, wA1); __builtin_amdgcn_sched_barrier(0);
;           SW_VA(dB0, dB1, wB0, wB1);    __builtin_amdgcn_sched_barrier(0);
;           SW_MF(3, dB0, dB1, wB0, wB1); __builtin_amdgcn_sched_barrier(0);
;           SW_VA(dA0, dA1, wA0, wA1);    __builtin_amdgcn_sched_barrier(0);
;           SW_VA(dB0, dB1, wB0, wB1); }
	v_mfma_f32_32x32x16_bf16 v[16:31], v[76:79], v[0:3], 0
	v_mfma_f32_32x32x16_bf16 v[16:31], v[72:75], v[4:7], v[16:31]
	ds_read_b128 v[0:3], v165 offset:384
	ds_read_b128 v[4:7], v165 offset:416
	v_pk_mul_f32 v[32:33], v[32:33], v[112:113] clamp
	v_pk_mul_f32 v[34:35], v[34:35], v[112:113] clamp
	v_pk_mul_f32 v[36:37], v[36:37], v[112:113] clamp
	v_pk_mul_f32 v[38:39], v[38:39], v[112:113] clamp
	v_pk_mul_f32 v[40:41], v[40:41], v[112:113] clamp
	v_pk_mul_f32 v[42:43], v[42:43], v[112:113] clamp
	v_pk_mul_f32 v[44:45], v[44:45], v[112:113] clamp
	v_pk_mul_f32 v[46:47], v[46:47], v[112:113] clamp
	v_pk_fma_f32 v[88:89], v[32:33], v[106:107], v[88:89] op_sel_hi:[1,0,1]
	v_pk_fma_f32 v[90:91], v[34:35], v[106:107], v[90:91] op_sel_hi:[1,0,1]
	v_pk_fma_f32 v[92:93], v[36:37], v[106:107], v[92:93] op_sel_hi:[1,0,1]
	v_pk_fma_f32 v[94:95], v[38:39], v[106:107], v[94:95] op_sel_hi:[1,0,1]
	v_pk_fma_f32 v[96:97], v[40:41], v[106:107], v[96:97] op_sel_hi:[1,0,1]
	v_pk_fma_f32 v[98:99], v[42:43], v[106:107], v[98:99] op_sel_hi:[1,0,1]
	v_pk_fma_f32 v[100:101], v[44:45], v[106:107], v[100:101] op_sel_hi:[1,0,1]
	v_pk_fma_f32 v[102:103], v[46:47], v[106:107], v[102:103] op_sel_hi:[1,0,1]
	s_waitcnt lgkmcnt(2)
	v_mfma_f32_32x32x16_bf16 v[32:47], v[76:79], v[8:11], 0
	v_mfma_f32_32x32x16_bf16 v[32:47], v[72:75], v[12:15], v[32:47]
	ds_read_b128 v[8:11], v165 offset:448
	ds_read_b128 v[12:15], v165 offset:480
	v_pk_mul_f32 v[16:17], v[16:17], v[112:113] clamp
	v_pk_mul_f32 v[18:19], v[18:19], v[112:113] clamp
	v_pk_mul_f32 v[20:21], v[20:21], v[112:113] clamp
	v_pk_mul_f32 v[22:23], v[22:23], v[112:113] clamp
	v_pk_mul_f32 v[24:25], v[24:25], v[112:113] clamp
	v_pk_mul_f32 v[26:27], v[26:27], v[112:113] clamp
	v_pk_mul_f32 v[28:29], v[28:29], v[112:113] clamp
	v_pk_mul_f32 v[30:31], v[30:31], v[112:113] clamp
	v_pk_fma_f32 v[88:89], v[16:17], v[84:85], v[88:89] op_sel_hi:[1,0,1]
	v_pk_fma_f32 v[90:91], v[18:19], v[84:85], v[90:91] op_sel_hi:[1,0,1]
	v_pk_fma_f32 v[92:93], v[20:21], v[84:85], v[92:93] op_sel_hi:[1,0,1]
	v_pk_fma_f32 v[94:95], v[22:23], v[84:85], v[94:95] op_sel_hi:[1,0,1]
	v_pk_fma_f32 v[96:97], v[24:25], v[84:85], v[96:97] op_sel_hi:[1,0,1]
	v_pk_fma_f32 v[98:99], v[26:27], v[84:85], v[98:99] op_sel_hi:[1,0,1]
	v_pk_fma_f32 v[100:101], v[28:29], v[84:85], v[100:101] op_sel_hi:[1,0,1]
	v_pk_fma_f32 v[102:103], v[30:31], v[84:85], v[102:103] op_sel_hi:[1,0,1]
	s_waitcnt lgkmcnt(2)
	v_mfma_f32_32x32x16_bf16 v[16:31], v[76:79], v[0:3], 0
	v_mfma_f32_32x32x16_bf16 v[16:31], v[72:75], v[4:7], v[16:31]
	ds_read_b128 v[0:3], v165
	ds_read_b128 v[4:7], v165 offset:32
	v_pk_mul_f32 v[32:33], v[32:33], v[112:113] clamp
	v_pk_mul_f32 v[34:35], v[34:35], v[112:113] clamp
	v_pk_mul_f32 v[36:37], v[36:37], v[112:113] clamp
	v_pk_mul_f32 v[38:39], v[38:39], v[112:113] clamp
	v_pk_mul_f32 v[40:41], v[40:41], v[112:113] clamp
	v_pk_mul_f32 v[42:43], v[42:43], v[112:113] clamp
	v_pk_mul_f32 v[44:45], v[44:45], v[112:113] clamp
	v_pk_mul_f32 v[46:47], v[46:47], v[112:113] clamp
	v_pk_fma_f32 v[88:89], v[32:33], v[108:109], v[88:89] op_sel_hi:[1,0,1]
	v_pk_fma_f32 v[90:91], v[34:35], v[108:109], v[90:91] op_sel_hi:[1,0,1]
	v_pk_fma_f32 v[92:93], v[36:37], v[108:109], v[92:93] op_sel_hi:[1,0,1]
	v_pk_fma_f32 v[94:95], v[38:39], v[108:109], v[94:95] op_sel_hi:[1,0,1]
	v_pk_fma_f32 v[96:97], v[40:41], v[108:109], v[96:97] op_sel_hi:[1,0,1]
	v_pk_fma_f32 v[98:99], v[42:43], v[108:109], v[98:99] op_sel_hi:[1,0,1]
	v_pk_fma_f32 v[100:101], v[44:45], v[108:109], v[100:101] op_sel_hi:[1,0,1]
	v_pk_fma_f32 v[102:103], v[46:47], v[108:109], v[102:103] op_sel_hi:[1,0,1]
	s_waitcnt lgkmcnt(2)
; __device__ __forceinline__ int bucketf(float f) { const unsigned u = __float_as_uint(f); const int idx = (int)((u >> 20) & 0x7FFu); const int c = min(max(idx - 816, 128), 255); return c ^ (((int)u >> 31) & 255); }
;     ...
;         { f32x16 zero16;
; #pragma unroll
;           for (int r = 0; r < 16; ++r) zero16[r] = 0.f;
;           f32x16 dA0, dA1, dB0, dB1; float wA0, wA1, wB0, wB1;
;           SW_MF(0, dA0, dA1, wA0, wA1);
;           SW_MF(1, dB0, dB1, wB0, wB1); __builtin_amdgcn_sched_barrier(0);
;           SW_VA(dA0, dA1, wA0, wA1);    __builtin_amdgcn_sched_barrier(0);
;           SW_MF(2, dA0, dA1, wA0, wA1); __builtin_amdgcn_sched_barrier(0);
;           SW_VA(dB0, dB1, wB0, wB1);    __builtin_amdgcn_sched_barrier(0);
;           SW_MF(3, dB0, dB1, wB0, wB1); __builtin_amdgcn_sched_barrier(0);
;           SW_VA(dA0, dA1, wA0, wA1);    __builtin_amdgcn_sched_barrier(0);
;           SW_VA(dB0, dB1, wB0, wB1); }
;     ...
;         f32x16 sc;
; #pragma unroll
;         for (int r = 0; r < 16; ++r) sc[r] = sc2[r >> 1][r & 1];
;         const unsigned s0 = (unsigned)(64 * kt + 32 * kb + 4 * hi);
; #pragma unroll
;         for (int r = 0; r < 16; ++r) { const unsigned s = s0 + (unsigned)((r & 3) + 8 * (r >> 2));
;             if (MODE == 5) { __hip_atomic_fetch_add(hist + 64 * bucketf(sc[r]), 1u, __ATOMIC_RELAXED, __HIP_MEMORY_SCOPE_WORKGROUP); continue; }
	v_mfma_f32_32x32x16_bf16 v[32:47], v[76:79], v[8:11], 0
	v_mfma_f32_32x32x16_bf16 v[32:47], v[72:75], v[12:15], v[32:47]
	ds_read_b128 v[8:11], v165 offset:64
	ds_read_b128 v[12:15], v165 offset:96
	v_pk_mul_f32 v[16:17], v[16:17], v[112:113] clamp
	v_pk_mul_f32 v[18:19], v[18:19], v[112:113] clamp
	v_pk_mul_f32 v[20:21], v[20:21], v[112:113] clamp
	v_pk_mul_f32 v[22:23], v[22:23], v[112:113] clamp
	v_pk_mul_f32 v[24:25], v[24:25], v[112:113] clamp
	v_pk_mul_f32 v[26:27], v[26:27], v[112:113] clamp
	v_pk_mul_f32 v[28:29], v[28:29], v[112:113] clamp
	v_pk_mul_f32 v[30:31], v[30:31], v[112:113] clamp
	v_pk_fma_f32 v[88:89], v[16:17], v[86:87], v[88:89] op_sel_hi:[1,0,1]
	v_pk_fma_f32 v[90:91], v[18:19], v[86:87], v[90:91] op_sel_hi:[1,0,1]
	v_pk_fma_f32 v[92:93], v[20:21], v[86:87], v[92:93] op_sel_hi:[1,0,1]
	v_pk_fma_f32 v[94:95], v[22:23], v[86:87], v[94:95] op_sel_hi:[1,0,1]
	v_pk_fma_f32 v[96:97], v[24:25], v[86:87], v[96:97] op_sel_hi:[1,0,1]
	v_pk_fma_f32 v[98:99], v[26:27], v[86:87], v[98:99] op_sel_hi:[1,0,1]
	v_pk_fma_f32 v[100:101], v[28:29], v[86:87], v[100:101] op_sel_hi:[1,0,1]
	v_pk_fma_f32 v[102:103], v[30:31], v[86:87], v[102:103] op_sel_hi:[1,0,1]
	v_pk_mul_f32 v[32:33], v[32:33], v[112:113] clamp
	v_pk_mul_f32 v[34:35], v[34:35], v[112:113] clamp
	v_pk_mul_f32 v[36:37], v[36:37], v[112:113] clamp
	v_pk_mul_f32 v[38:39], v[38:39], v[112:113] clamp
	v_pk_mul_f32 v[40:41], v[40:41], v[112:113] clamp
	v_pk_mul_f32 v[42:43], v[42:43], v[112:113] clamp
	v_pk_mul_f32 v[44:45], v[44:45], v[112:113] clamp
	v_pk_mul_f32 v[46:47], v[46:47], v[112:113] clamp
	v_pk_fma_f32 v[88:89], v[32:33], v[110:111], v[88:89] op_sel_hi:[1,0,1]
	v_pk_fma_f32 v[90:91], v[34:35], v[110:111], v[90:91] op_sel_hi:[1,0,1]
	v_pk_fma_f32 v[92:93], v[36:37], v[110:111], v[92:93] op_sel_hi:[1,0,1]
	v_pk_fma_f32 v[94:95], v[38:39], v[110:111], v[94:95] op_sel_hi:[1,0,1]
	v_pk_fma_f32 v[96:97], v[40:41], v[110:111], v[96:97] op_sel_hi:[1,0,1]
	v_pk_fma_f32 v[98:99], v[42:43], v[110:111], v[98:99] op_sel_hi:[1,0,1]
	v_pk_fma_f32 v[100:101], v[44:45], v[110:111], v[100:101] op_sel_hi:[1,0,1]
	v_pk_fma_f32 v[102:103], v[46:47], v[110:111], v[102:103] op_sel_hi:[1,0,1]
	s_waitcnt lgkmcnt(0)
	v_bfe_u32 v48, v88, 20, 11
	v_ashrrev_i32_e32 v49, 31, v88
	v_med3_u32 v48, v48, v117, v118
	v_bitop3_b32 v48, v48, v49, s56 bitop3:0x78
	v_lshl_add_u32 v48, v48, 8, v116
	ds_add_u32 v48, v222
	v_bfe_u32 v50, v89, 20, 11
	v_ashrrev_i32_e32 v51, 31, v89
	v_med3_u32 v50, v50, v117, v118
	v_bitop3_b32 v50, v50, v51, s56 bitop3:0x78
	v_lshl_add_u32 v50, v50, 8, v116
	ds_add_u32 v50, v222
	v_bfe_u32 v52, v90, 20, 11
	v_ashrrev_i32_e32 v53, 31, v90
	v_med3_u32 v52, v52, v117, v118
	v_bitop3_b32 v52, v52, v53, s56 bitop3:0x78
	v_lshl_add_u32 v52, v52, 8, v116
	ds_add_u32 v52, v222
	v_bfe_u32 v54, v91, 20, 11
	v_ashrrev_i32_e32 v55, 31, v91
	v_med3_u32 v54, v54, v117, v118
	v_bitop3_b32 v54, v54, v55, s56 bitop3:0x78
	v_lshl_add_u32 v54, v54, 8, v116
	ds_add_u32 v54, v222
	v_bfe_u32 v48, v92, 20, 11
	v_ashrrev_i32_e32 v49, 31, v92
	v_med3_u32 v48, v48, v117, v118
	v_bitop3_b32 v48, v48, v49, s56 bitop3:0x78
	v_lshl_add_u32 v48, v48, 8, v116
	ds_add_u32 v48, v222
	v_bfe_u32 v50, v93, 20, 11
	v_ashrrev_i32_e32 v51, 31, v93
	v_med3_u32 v50, v50, v117, v118
	v_bitop3_b32 v50, v50, v51, s56 bitop3:0x78
	v_lshl_add_u32 v50, v50, 8, v116
	ds_add_u32 v50, v222
	v_bfe_u32 v52, v94, 20, 11
	v_ashrrev_i32_e32 v53, 31, v94
	v_med3_u32 v52, v52, v117, v118
	v_bitop3_b32 v52, v52, v53, s56 bitop3:0x78
	v_lshl_add_u32 v52, v52, 8, v116
	ds_add_u32 v52, v222
	v_bfe_u32 v54, v95, 20, 11
	v_ashrrev_i32_e32 v55, 31, v95
	v_med3_u32 v54, v54, v117, v118
	v_bitop3_b32 v54, v54, v55, s56 bitop3:0x78
	v_lshl_add_u32 v54, v54, 8, v116
	ds_add_u32 v54, v222
	v_bfe_u32 v48, v96, 20, 11
	v_ashrrev_i32_e32 v49, 31, v96
	v_med3_u32 v48, v48, v117, v118
	v_bitop3_b32 v48, v48, v49, s56 bitop3:0x78
	v_lshl_add_u32 v48, v48, 8, v116
	ds_add_u32 v48, v222
	v_bfe_u32 v50, v97, 20, 11
	v_ashrrev_i32_e32 v51, 31, v97
	v_med3_u32 v50, v50, v117, v118
	v_bitop3_b32 v50, v50, v51, s56 bitop3:0x78
	v_lshl_add_u32 v50, v50, 8, v116
	ds_add_u32 v50, v222
	v_bfe_u32 v52, v98, 20, 11
	v_ashrrev_i32_e32 v53, 31, v98
	v_med3_u32 v52, v52, v117, v118
	v_bitop3_b32 v52, v52, v53, s56 bitop3:0x78
	v_lshl_add_u32 v52, v52, 8, v116
	ds_add_u32 v52, v222
	v_bfe_u32 v54, v99, 20, 11
	v_ashrrev_i32_e32 v55, 31, v99
	v_med3_u32 v54, v54, v117, v118
	v_bitop3_b32 v54, v54, v55, s56 bitop3:0x78
	v_lshl_add_u32 v54, v54, 8, v116
	ds_add_u32 v54, v222
	v_bfe_u32 v48, v100, 20, 11
	v_ashrrev_i32_e32 v49, 31, v100
	v_med3_u32 v48, v48, v117, v118
	v_bitop3_b32 v48, v48, v49, s56 bitop3:0x78
	v_lshl_add_u32 v48, v48, 8, v116
	ds_add_u32 v48, v222
	v_bfe_u32 v50, v101, 20, 11
	v_ashrrev_i32_e32 v51, 31, v101
	v_med3_u32 v50, v50, v117, v118
	v_bitop3_b32 v50, v50, v51, s56 bitop3:0x78
	v_lshl_add_u32 v50, v50, 8, v116
	ds_add_u32 v50, v222
	v_bfe_u32 v52, v102, 20, 11
	v_ashrrev_i32_e32 v53, 31, v102
	v_med3_u32 v52, v52, v117, v118
	v_bitop3_b32 v52, v52, v53, s56 bitop3:0x78
	v_lshl_add_u32 v52, v52, 8, v116
	ds_add_u32 v52, v222
	v_bfe_u32 v54, v103, 20, 11
	v_ashrrev_i32_e32 v55, 31, v103
	v_med3_u32 v54, v54, v117, v118
	v_bitop3_b32 v54, v54, v55, s56 bitop3:0x78
	v_lshl_add_u32 v54, v54, 8, v116
	ds_add_u32 v54, v222
	s_waitcnt vmcnt(0)
	v_mov_b64_e32 v[76:77], v[64:65]
	v_mov_b64_e32 v[78:79], v[66:67]
	v_mov_b64_e32 v[72:73], v[68:69]
	v_mov_b64_e32 v[74:75], v[70:71]
	s_cmp_lg_u32 s25, s1
	s_mov_b32 s2, s1
	s_cbranch_scc1 .Lm5_loop

; #define LAS __attribute__((address_space(3)))
;     constexpr int SHIFT = 24 - 8 * (MODE & 3);
;     const int r32 = lane & 31, hi = lane >> 5, ql = 32 * (wid & 1) + r32;
;     LAS unsigned* hist = (LAS unsigned*)(lds + DS_HIST) + ql;   LAS unsigned short* sel = (LAS unsigned short*)(lds + DS_SEL) + ql * 256; LAS unsigned* cnt = (LAS unsigned*)(lds + DS_CNT) + ql;
;     LAS unsigned* cand = (LAS unsigned*)(lds + DS_CAND) + ql * DS_CAP; LAS unsigned* ccnt = (LAS unsigned*)(lds + DS_CCNT) + ql;
;     LAS const unsigned char* iqb = lds + DS_IQ + ql * 528 + hi * 16; LAS const float* wqb = (LAS const float*)(lds + DS_WQ) + ql;
;     const int kt0 = wid >> 1; const int nit = kt0 <= c ? 2 * ((c - kt0) / 4 + 1) : 0;
;     const float t_lo = bucket_lo((int)pref), t_hi = bucket_lo((int)pref + 1);
;     const bf16_t* ikp = Zb + (size_t)(64 * kt0 + r32) * NZ + ZIK + hi * 8;
;     bf16x8 a0, a1;
;     if (nit > 0) { a0 = *(const bf16x8*)ikp; a1 = *(const bf16x8*)(ikp + 16); }
; #pragma unroll 1
;     for (int it = 0; it < nit; ++it) {
;         const int kt = kt0 + 4 * (it >> 1), kb = it & 1;
;         const int itn = it + 1 < nit ? it + 1 : it;
;         const bf16_t* np = ikp + (size_t)(256 * (itn >> 1) + 32 * (itn & 1)) * NZ; const bf16x8 n0 = *(const bf16x8*)np, n1 = *(const bf16x8*)(np + 16);
;         f32x2v sc2[8];
; #pragma unroll
;         for (int r = 0; r < 8; ++r) sc2[r] = (f32x2v){0.f, 0.f};
;     ...
;         { f32x16 zero16;
; #pragma unroll
;           for (int r = 0; r < 16; ++r) zero16[r] = 0.f;
;           f32x16 dA0, dA1, dB0, dB1; float wA0, wA1, wB0, wB1;
;           SW_MF(0, dA0, dA1, wA0, wA1);
;           SW_MF(1, dB0, dB1, wB0, wB1); __builtin_amdgcn_sched_barrier(0);
;           SW_VA(dA0, dA1, wA0, wA1);    __builtin_amdgcn_sched_barrier(0);
;           SW_MF(2, dA0, dA1, wA0, wA1); __builtin_amdgcn_sched_barrier(0);
;           SW_VA(dB0, dB1, wB0, wB1);    __builtin_amdgcn_sched_barrier(0);
;           SW_MF(3, dB0, dB1, wB0, wB1); __builtin_amdgcn_sched_barrier(0);
;           SW_VA(dA0, dA1, wA0, wA1);    __builtin_amdgcn_sched_barrier(0);
;           SW_VA(dB0, dB1, wB0, wB1); }
.LBB0_1521:
	s_and_b64 vcc, exec, s[18:19]
	s_cbranch_vccnz .LBB0_1620
	v_lshl_add_u32 v179, v169, 9, s57
	v_add_u32_e32 v180, s94, v171
	v_lshl_add_u32 v169, v169, 10, v200
	v_add_u32_e32 v171, s33, v171
	v_mul_f32_e32 v122, 0x2c800000, v154
	v_mul_f32_e32 v123, 0x2c800000, v178
	s_mov_b32 s18, 0
	v_mov_b32_e32 v112, 0x2c800000
	v_mov_b32_e32 v113, 0x2c800000
	ds_read2st64_b32 v[80:81], v167 offset1:1
	ds_read2st64_b32 v[82:83], v167 offset0:2 offset1:3
	ds_read2st64_b32 v[84:85], v167 offset0:4 offset1:5
	ds_read2st64_b32 v[86:87], v167 offset0:6 offset1:7
	ds_read_b128 v[0:3], v165
	ds_read_b128 v[4:7], v165 offset:32
	ds_read_b128 v[8:11], v165 offset:64
	ds_read_b128 v[12:15], v165 offset:96
	s_waitcnt lgkmcnt(4)
	v_mov_b32_e32 v104, v81
	v_mov_b32_e32 v106, v83
	v_mov_b32_e32 v108, v85
	v_mov_b32_e32 v110, v87
	s_waitcnt vmcnt(0) lgkmcnt(0)
.Lm6_loop:
	v_mfma_f32_32x32x16_bf16 v[16:31], v[132:135], v[0:3], 0
	v_mfma_f32_32x32x16_bf16 v[16:31], v[128:131], v[4:7], v[16:31]
	ds_read_b128 v[0:3], v165 offset:128
	ds_read_b128 v[4:7], v165 offset:160
	v_mfma_f32_32x32x16_bf16 v[32:47], v[132:135], v[8:11], 0
	v_mfma_f32_32x32x16_bf16 v[32:47], v[128:131], v[12:15], v[32:47]
	ds_read_b128 v[8:11], v165 offset:192
	ds_read_b128 v[12:15], v165 offset:224
	s_add_i32 s1, s18, 1
	s_cmp_lt_u32 s1, s25
	s_cselect_b32 s3, s1, s18
	s_lshl_b32 vcc_lo, s3, 7
	s_and_b32 vcc_lo, vcc_lo, 0x7fffff00
	s_lshl_b32 s3, s3, 5
	s_and_b32 s3, s3, 32
	s_or_b32 s3, vcc_lo, s3
	v_mad_u64_u32 v[114:115], vcc, s3, v223, v[140:141]
	s_lshr_b32 s0, s18, 1
	s_lshl_b32 s0, s0, 2
	s_add_i32 s0, s0, s24
	s_lshl_b32 s0, s0, 6
	s_and_b32 s2, s18, 1
	s_lshl_b32 s2, s2, 5
	s_or_b32 s0, s0, s2
	v_or_b32_e32 v124, s0, v159
	global_load_dwordx4 v[64:67], v[114:115], off
	global_load_dwordx4 v[68:71], v[114:115], off offset:32
	v_pk_mul_f32 v[16:17], v[16:17], v[112:113] clamp
	v_pk_mul_f32 v[18:19], v[18:19], v[112:113] clamp
	v_pk_mul_f32 v[20:21], v[20:21], v[112:113] clamp
	v_pk_mul_f32 v[22:23], v[22:23], v[112:113] clamp
	v_pk_mul_f32 v[24:25], v[24:25], v[112:113] clamp
	v_pk_mul_f32 v[26:27], v[26:27], v[112:113] clamp
	v_pk_mul_f32 v[28:29], v[28:29], v[112:113] clamp
	v_pk_mul_f32 v[30:31], v[30:31], v[112:113] clamp
	v_pk_fma_f32 v[88:89], v[16:17], v[80:81], 0 op_sel_hi:[1,0,0]
	v_pk_fma_f32 v[90:91], v[18:19], v[80:81], 0 op_sel_hi:[1,0,0]
	v_pk_fma_f32 v[92:93], v[20:21], v[80:81], 0 op_sel_hi:[1,0,0]
	v_pk_fma_f32 v[94:95], v[22:23], v[80:81], 0 op_sel_hi:[1,0,0]
	v_pk_fma_f32 v[96:97], v[24:25], v[80:81], 0 op_sel_hi:[1,0,0]
	v_pk_fma_f32 v[98:99], v[26:27], v[80:81], 0 op_sel_hi:[1,0,0]
	v_pk_fma_f32 v[100:101], v[28:29], v[80:81], 0 op_sel_hi:[1,0,0]
	v_pk_fma_f32 v[102:103], v[30:31], v[80:81], 0 op_sel_hi:[1,0,0]
	s_waitcnt lgkmcnt(2)
	v_mfma_f32_32x32x16_bf16 v[16:31], v[132:135], v[0:3], 0
	v_mfma_f32_32x32x16_bf16 v[16:31], v[128:131], v[4:7], v[16:31]
	ds_read_b128 v[0:3], v165 offset:256
	ds_read_b128 v[4:7], v165 offset:288
	v_pk_mul_f32 v[32:33], v[32:33], v[112:113] clamp
	v_pk_mul_f32 v[34:35], v[34:35], v[112:113] clamp
	v_pk_mul_f32 v[36:37], v[36:37], v[112:113] clamp
	v_pk_mul_f32 v[38:39], v[38:39], v[112:113] clamp
	v_pk_mul_f32 v[40:41], v[40:41], v[112:113] clamp
	v_pk_mul_f32 v[42:43], v[42:43], v[112:113] clamp
	v_pk_mul_f32 v[44:45], v[44:45], v[112:113] clamp
	v_pk_mul_f32 v[46:47], v[46:47], v[112:113] clamp
	v_pk_fma_f32 v[88:89], v[32:33], v[104:105], v[88:89] op_sel_hi:[1,0,1]
	v_pk_fma_f32 v[90:91], v[34:35], v[104:105], v[90:91] op_sel_hi:[1,0,1]
	v_pk_fma_f32 v[92:93], v[36:37], v[104:105], v[92:93] op_sel_hi:[1,0,1]
	v_pk_fma_f32 v[94:95], v[38:39], v[104:105], v[94:95] op_sel_hi:[1,0,1]
	v_pk_fma_f32 v[96:97], v[40:41], v[104:105], v[96:97] op_sel_hi:[1,0,1]
	v_pk_fma_f32 v[98:99], v[42:43], v[104:105], v[98:99] op_sel_hi:[1,0,1]
	v_pk_fma_f32 v[100:101], v[44:45], v[104:105], v[100:101] op_sel_hi:[1,0,1]
	v_pk_fma_f32 v[102:103], v[46:47], v[104:105], v[102:103] op_sel_hi:[1,0,1]
	s_waitcnt lgkmcnt(2)
	v_mfma_f32_32x32x16_bf16 v[32:47], v[132:135], v[8:11], 0
	v_mfma_f32_32x32x16_bf16 v[32:47], v[128:131], v[12:15], v[32:47]
	ds_read_b128 v[8:11], v165 offset:320
	ds_read_b128 v[12:15], v165 offset:352
	v_pk_mul_f32 v[16:17], v[16:17], v[112:113] clamp
	v_pk_mul_f32 v[18:19], v[18:19], v[112:113] clamp
	v_pk_mul_f32 v[20:21], v[20:21], v[112:113] clamp
	v_pk_mul_f32 v[22:23], v[22:23], v[112:113] clamp
	v_pk_mul_f32 v[24:25], v[24:25], v[112:113] clamp
	v_pk_mul_f32 v[26:27], v[26:27], v[112:113] clamp
	v_pk_mul_f32 v[28:29], v[28:29], v[112:113] clamp
	v_pk_mul_f32 v[30:31], v[30:31], v[112:113] clamp
	v_pk_fma_f32 v[88:89], v[16:17], v[82:83], v[88:89] op_sel_hi:[1,0,1]
	v_pk_fma_f32 v[90:91], v[18:19], v[82:83], v[90:91] op_sel_hi:[1,0,1]
	v_pk_fma_f32 v[92:93], v[20:21], v[82:83], v[92:93] op_sel_hi:[1,0,1]
	v_pk_fma_f32 v[94:95], v[22:23], v[82:83], v[94:95] op_sel_hi:[1,0,1]
	v_pk_fma_f32 v[96:97], v[24:25], v[82:83], v[96:97] op_sel_hi:[1,0,1]
	v_pk_fma_f32 v[98:99], v[26:27], v[82:83], v[98:99] op_sel_hi:[1,0,1]
	v_pk_fma_f32 v[100:101], v[28:29], v[82:83], v[100:101] op_sel_hi:[1,0,1]
	v_pk_fma_f32 v[102:103], v[30:31], v[82:83], v[102:103] op_sel_hi:[1,0,1]
	s_waitcnt lgkmcnt(2)
; __device__ __forceinline__ unsigned sortable(float f) { const unsigned u = __float_as_uint(f); return u ^ ((unsigned)((int)u >> 31) | 0x80000000u); }
; __device__ __forceinline__ int bucketf(float f) { const unsigned u = __float_as_uint(f); const int idx = (int)((u >> 20) & 0x7FFu); const int c = min(max(idx - 816, 128), 255); return c ^ (((int)u >> 31) & 255); }
;     ...
;         { f32x16 zero16;
; #pragma unroll
;           for (int r = 0; r < 16; ++r) zero16[r] = 0.f;
;           f32x16 dA0, dA1, dB0, dB1; float wA0, wA1, wB0, wB1;
;           SW_MF(0, dA0, dA1, wA0, wA1);
;           SW_MF(1, dB0, dB1, wB0, wB1); __builtin_amdgcn_sched_barrier(0);
;           SW_VA(dA0, dA1, wA0, wA1);    __builtin_amdgcn_sched_barrier(0);
;           SW_MF(2, dA0, dA1, wA0, wA1); __builtin_amdgcn_sched_barrier(0);
;           SW_VA(dB0, dB1, wB0, wB1);    __builtin_amdgcn_sched_barrier(0);
;           SW_MF(3, dB0, dB1, wB0, wB1); __builtin_amdgcn_sched_barrier(0);
;           SW_VA(dA0, dA1, wA0, wA1);    __builtin_amdgcn_sched_barrier(0);
;           SW_VA(dB0, dB1, wB0, wB1); }
;     ...
;         f32x16 sc;
; #pragma unroll
;         for (int r = 0; r < 16; ++r) sc[r] = sc2[r >> 1][r & 1];
;         const unsigned s0 = (unsigned)(64 * kt + 32 * kb + 4 * hi);
; #pragma unroll
;         for (int r = 0; r < 16; ++r) { const unsigned s = s0 + (unsigned)((r & 3) + 8 * (r >> 2));
;             if (MODE == 5) { __hip_atomic_fetch_add(hist + 64 * bucketf(sc[r]), 1u, __ATOMIC_RELAXED, __HIP_MEMORY_SCOPE_WORKGROUP); continue; }
;             if (MODE == 6) {
;                 if (sc[r] >= t_hi) { const unsigned pos = __hip_atomic_fetch_add(cnt, 1u, __ATOMIC_RELAXED, __HIP_MEMORY_SCOPE_WORKGROUP); sel[pos & 255u] = (unsigned short)s; }
;                 else if (sc[r] >= t_lo) { const unsigned key = (sortable(sc[r]) & 0xFFFFE000u) | (8191u - s);
;                     const unsigned pos = __hip_atomic_fetch_add(ccnt, 1u, __ATOMIC_RELAXED, __HIP_MEMORY_SCOPE_WORKGROUP); cand[pos & (DS_CAP - 1)] = key; }
	v_mfma_f32_32x32x16_bf16 v[16:31], v[132:135], v[0:3], 0
	v_mfma_f32_32x32x16_bf16 v[16:31], v[128:131], v[4:7], v[16:31]
	ds_read_b128 v[0:3], v165 offset:384
	ds_read_b128 v[4:7], v165 offset:416
	v_pk_mul_f32 v[32:33], v[32:33], v[112:113] clamp
	v_pk_mul_f32 v[34:35], v[34:35], v[112:113] clamp
	v_pk_mul_f32 v[36:37], v[36:37], v[112:113] clamp
	v_pk_mul_f32 v[38:39], v[38:39], v[112:113] clamp
	v_pk_mul_f32 v[40:41], v[40:41], v[112:113] clamp
	v_pk_mul_f32 v[42:43], v[42:43], v[112:113] clamp
	v_pk_mul_f32 v[44:45], v[44:45], v[112:113] clamp
	v_pk_mul_f32 v[46:47], v[46:47], v[112:113] clamp
	v_pk_fma_f32 v[88:89], v[32:33], v[106:107], v[88:89] op_sel_hi:[1,0,1]
	v_pk_fma_f32 v[90:91], v[34:35], v[106:107], v[90:91] op_sel_hi:[1,0,1]
	v_pk_fma_f32 v[92:93], v[36:37], v[106:107], v[92:93] op_sel_hi:[1,0,1]
	v_pk_fma_f32 v[94:95], v[38:39], v[106:107], v[94:95] op_sel_hi:[1,0,1]
	v_pk_fma_f32 v[96:97], v[40:41], v[106:107], v[96:97] op_sel_hi:[1,0,1]
	v_pk_fma_f32 v[98:99], v[42:43], v[106:107], v[98:99] op_sel_hi:[1,0,1]
	v_pk_fma_f32 v[100:101], v[44:45], v[106:107], v[100:101] op_sel_hi:[1,0,1]
	v_pk_fma_f32 v[102:103], v[46:47], v[106:107], v[102:103] op_sel_hi:[1,0,1]
	s_waitcnt lgkmcnt(2)
	v_mfma_f32_32x32x16_bf16 v[32:47], v[132:135], v[8:11], 0
	v_mfma_f32_32x32x16_bf16 v[32:47], v[128:131], v[12:15], v[32:47]
	ds_read_b128 v[8:11], v165 offset:448
	ds_read_b128 v[12:15], v165 offset:480
	v_pk_mul_f32 v[16:17], v[16:17], v[112:113] clamp
	v_pk_mul_f32 v[18:19], v[18:19], v[112:113] clamp
	v_pk_mul_f32 v[20:21], v[20:21], v[112:113] clamp
	v_pk_mul_f32 v[22:23], v[22:23], v[112:113] clamp
	v_pk_mul_f32 v[24:25], v[24:25], v[112:113] clamp
	v_pk_mul_f32 v[26:27], v[26:27], v[112:113] clamp
	v_pk_mul_f32 v[28:29], v[28:29], v[112:113] clamp
	v_pk_mul_f32 v[30:31], v[30:31], v[112:113] clamp
	v_pk_fma_f32 v[88:89], v[16:17], v[84:85], v[88:89] op_sel_hi:[1,0,1]
	v_pk_fma_f32 v[90:91], v[18:19], v[84:85], v[90:91] op_sel_hi:[1,0,1]
	v_pk_fma_f32 v[92:93], v[20:21], v[84:85], v[92:93] op_sel_hi:[1,0,1]
	v_pk_fma_f32 v[94:95], v[22:23], v[84:85], v[94:95] op_sel_hi:[1,0,1]
	v_pk_fma_f32 v[96:97], v[24:25], v[84:85], v[96:97] op_sel_hi:[1,0,1]
	v_pk_fma_f32 v[98:99], v[26:27], v[84:85], v[98:99] op_sel_hi:[1,0,1]
	v_pk_fma_f32 v[100:101], v[28:29], v[84:85], v[100:101] op_sel_hi:[1,0,1]
	v_pk_fma_f32 v[102:103], v[30:31], v[84:85], v[102:103] op_sel_hi:[1,0,1]
	s_waitcnt lgkmcnt(2)
	v_mfma_f32_32x32x16_bf16 v[16:31], v[132:135], v[0:3], 0
	v_mfma_f32_32x32x16_bf16 v[16:31], v[128:131], v[4:7], v[16:31]
	ds_read_b128 v[0:3], v165
	ds_read_b128 v[4:7], v165 offset:32
	v_pk_mul_f32 v[32:33], v[32:33], v[112:113] clamp
	v_pk_mul_f32 v[34:35], v[34:35], v[112:113] clamp
	v_pk_mul_f32 v[36:37], v[36:37], v[112:113] clamp
	v_pk_mul_f32 v[38:39], v[38:39], v[112:113] clamp
	v_pk_mul_f32 v[40:41], v[40:41], v[112:113] clamp
	v_pk_mul_f32 v[42:43], v[42:43], v[112:113] clamp
	v_pk_mul_f32 v[44:45], v[44:45], v[112:113] clamp
	v_pk_mul_f32 v[46:47], v[46:47], v[112:113] clamp
	v_pk_fma_f32 v[88:89], v[32:33], v[108:109], v[88:89] op_sel_hi:[1,0,1]
	v_pk_fma_f32 v[90:91], v[34:35], v[108:109], v[90:91] op_sel_hi:[1,0,1]
	v_pk_fma_f32 v[92:93], v[36:37], v[108:109], v[92:93] op_sel_hi:[1,0,1]
	v_pk_fma_f32 v[94:95], v[38:39], v[108:109], v[94:95] op_sel_hi:[1,0,1]
	v_pk_fma_f32 v[96:97], v[40:41], v[108:109], v[96:97] op_sel_hi:[1,0,1]
	v_pk_fma_f32 v[98:99], v[42:43], v[108:109], v[98:99] op_sel_hi:[1,0,1]
	v_pk_fma_f32 v[100:101], v[44:45], v[108:109], v[100:101] op_sel_hi:[1,0,1]
	v_pk_fma_f32 v[102:103], v[46:47], v[108:109], v[102:103] op_sel_hi:[1,0,1]
	s_waitcnt lgkmcnt(2)
	v_mfma_f32_32x32x16_bf16 v[32:47], v[132:135], v[8:11], 0
	v_mfma_f32_32x32x16_bf16 v[32:47], v[128:131], v[12:15], v[32:47]
	ds_read_b128 v[8:11], v165 offset:64
	ds_read_b128 v[12:15], v165 offset:96
	v_pk_mul_f32 v[16:17], v[16:17], v[112:113] clamp
	v_pk_mul_f32 v[18:19], v[18:19], v[112:113] clamp
	v_pk_mul_f32 v[20:21], v[20:21], v[112:113] clamp
	v_pk_mul_f32 v[22:23], v[22:23], v[112:113] clamp
	v_pk_mul_f32 v[24:25], v[24:25], v[112:113] clamp
	v_pk_mul_f32 v[26:27], v[26:27], v[112:113] clamp
	v_pk_mul_f32 v[28:29], v[28:29], v[112:113] clamp
	v_pk_mul_f32 v[30:31], v[30:31], v[112:113] clamp
	v_pk_fma_f32 v[88:89], v[16:17], v[86:87], v[88:89] op_sel_hi:[1,0,1]
	v_pk_fma_f32 v[90:91], v[18:19], v[86:87], v[90:91] op_sel_hi:[1,0,1]
	v_pk_fma_f32 v[92:93], v[20:21], v[86:87], v[92:93] op_sel_hi:[1,0,1]
	v_pk_fma_f32 v[94:95], v[22:23], v[86:87], v[94:95] op_sel_hi:[1,0,1]
	v_pk_fma_f32 v[96:97], v[24:25], v[86:87], v[96:97] op_sel_hi:[1,0,1]
	v_pk_fma_f32 v[98:99], v[26:27], v[86:87], v[98:99] op_sel_hi:[1,0,1]
	v_pk_fma_f32 v[100:101], v[28:29], v[86:87], v[100:101] op_sel_hi:[1,0,1]
	v_pk_fma_f32 v[102:103], v[30:31], v[86:87], v[102:103] op_sel_hi:[1,0,1]
	v_pk_mul_f32 v[32:33], v[32:33], v[112:113] clamp
	v_pk_mul_f32 v[34:35], v[34:35], v[112:113] clamp
	v_pk_mul_f32 v[36:37], v[36:37], v[112:113] clamp
	v_pk_mul_f32 v[38:39], v[38:39], v[112:113] clamp
	v_pk_mul_f32 v[40:41], v[40:41], v[112:113] clamp
	v_pk_mul_f32 v[42:43], v[42:43], v[112:113] clamp
	v_pk_mul_f32 v[44:45], v[44:45], v[112:113] clamp
	v_pk_mul_f32 v[46:47], v[46:47], v[112:113] clamp
	v_pk_fma_f32 v[88:89], v[32:33], v[110:111], v[88:89] op_sel_hi:[1,0,1]
	v_pk_fma_f32 v[90:91], v[34:35], v[110:111], v[90:91] op_sel_hi:[1,0,1]
	v_pk_fma_f32 v[92:93], v[36:37], v[110:111], v[92:93] op_sel_hi:[1,0,1]
	v_pk_fma_f32 v[94:95], v[38:39], v[110:111], v[94:95] op_sel_hi:[1,0,1]
	v_pk_fma_f32 v[96:97], v[40:41], v[110:111], v[96:97] op_sel_hi:[1,0,1]
	v_pk_fma_f32 v[98:99], v[42:43], v[110:111], v[98:99] op_sel_hi:[1,0,1]
	v_pk_fma_f32 v[100:101], v[44:45], v[110:111], v[100:101] op_sel_hi:[1,0,1]
	v_pk_fma_f32 v[102:103], v[46:47], v[110:111], v[102:103] op_sel_hi:[1,0,1]
	s_waitcnt lgkmcnt(0)
	v_cmp_ge_f32_e64 s[40:41], v88, v122
	v_cmp_ge_f32_e64 s[42:43], v88, v123
	v_mov_b32_e32 v18, v124
	s_andn2_b64 s[42:43], s[42:43], s[40:41]
	s_mov_b64 exec, s[40:41]
	ds_add_rtn_u32 v16, v180, v222
	s_mov_b64 exec, s[42:43]
	ds_add_rtn_u32 v16, v171, v222
	s_mov_b64 exec, -1
	v_cmp_ge_f32_e64 s[44:45], v89, v122
	v_cmp_ge_f32_e64 s[22:23], v89, v123
	v_or_b32_e32 v19, 1, v124
	s_andn2_b64 s[22:23], s[22:23], s[44:45]
	s_mov_b64 exec, s[44:45]
	ds_add_rtn_u32 v17, v180, v222
	s_mov_b64 exec, s[22:23]
	ds_add_rtn_u32 v17, v171, v222
	s_mov_b64 exec, -1
	v_cmp_ge_f32_e64 s[20:21], v90, v122
	v_cmp_ge_f32_e64 s[2:3], v90, v123
	v_or_b32_e32 v24, 2, v124
	s_andn2_b64 s[2:3], s[2:3], s[20:21]
	s_mov_b64 exec, s[20:21]
	ds_add_rtn_u32 v23, v180, v222
	s_mov_b64 exec, s[2:3]
	ds_add_rtn_u32 v23, v171, v222
	s_mov_b64 exec, -1
	s_waitcnt lgkmcnt(4)
	v_and_b32_e32 v16, 0xff, v16
	s_mov_b64 exec, s[40:41]
	v_lshl_add_u32 v20, v16, 1, v179
	ds_write_b16 v20, v18
	s_mov_b64 exec, s[42:43]
	s_cbranch_execz .Lm6_nb0
; __device__ __forceinline__ unsigned sortable(float f) { const unsigned u = __float_as_uint(f); return u ^ ((unsigned)((int)u >> 31) | 0x80000000u); }
;     ...
;                 else if (sc[r] >= t_lo) { const unsigned key = (sortable(sc[r]) & 0xFFFFE000u) | (8191u - s);
;                     const unsigned pos = __hip_atomic_fetch_add(ccnt, 1u, __ATOMIC_RELAXED, __HIP_MEMORY_SCOPE_WORKGROUP); cand[pos & (DS_CAP - 1)] = key; }
	v_ashrrev_i32_e32 v22, 31, v88
	v_sub_u32_e32 v18, 0x1fff, v18
	v_lshl_add_u32 v20, v16, 2, v169
	v_bitop3_b32 v21, v22, v88, s64 bitop3:0x36
	v_and_or_b32 v21, v21, s65, v18
	ds_write_b32 v20, v21
